# accumulator clears between tiles use v_mov_b64 (64 instead of 127 moves per tile)
# speedup vs baseline: 1.0312x; 1.0019x over previous
; template <class Epi>
; __device__ __forceinline__ void gemm_phase(LAS unsigned char* lds, const Gemm g, const StaticOrder& S, const Epi& E) {
;     ...
;         const bool has_next = S.next(ui + 1, nxt);
;         const char* nA = has_next ? (const char*)g.A + (size_t)nxt.pm * tstep : cA; const char* nB = has_next ? (const char*)g.Bt + (size_t)nxt.pn * tstep : cB;
;     ...
; #pragma unroll
;         for (int a = 0; a < 2; ++a)
; #pragma unroll
;             for (int b = 0; b < 2; ++b)
; #pragma unroll
;                 for (int m = 0; m < 4; ++m)
; #pragma unroll
;                     for (int n = 0; n < 2; ++n) acc[a][b][m][n] = (f32x4){0.f, 0.f, 0.f, 0.f};
;         cur = nxt; cA = nA; cB = nB; ++ui;
.LBB0_42:
	v_mov_b64_e32 v[0:1], 0x500
	s_ashr_i32 s15, s14, 31
	v_cmp_lt_i64_e32 vcc, s[16:17], v[0:1]
	s_lshl_b64 s[16:17], s[14:15], 19
	s_add_u32 s16, s30, s16
	s_addc_u32 s17, s31, s17
	s_and_b64 s[18:19], vcc, exec
	s_cselect_b32 s3, s17, s23
	s_cselect_b32 s9, s16, s22
	s_ashr_i32 s13, s12, 31
	s_lshl_b64 s[18:19], s[12:13], 19
	s_add_u32 s18, s34, s18
	s_addc_u32 s19, s35, s19
	s_and_b64 s[26:27], vcc, exec
	s_cselect_b32 s13, s19, s25
	s_cselect_b32 s15, s18, s24
	s_add_u32 s22, s22, 0x40080
	s_addc_u32 s23, s23, 0
	s_add_u32 s43, s24, 0x100
	v_mov_b32_e32 v0, 0
	s_addc_u32 s45, s25, 0
	s_mov_b32 s46, -2
	v_mov_b32_e32 v1, v0
	v_mov_b64_e32 v[2:3], 0
	v_mov_b64_e32 v[4:5], 0
	v_mov_b64_e32 v[6:7], 0
	v_mov_b64_e32 v[12:13], 0
	v_mov_b64_e32 v[14:15], 0
	v_mov_b64_e32 v[20:21], 0
	v_mov_b64_e32 v[22:23], 0
	v_mov_b64_e32 v[32:33], 0
	v_mov_b64_e32 v[34:35], 0
	v_mov_b64_e32 v[36:37], 0
	v_mov_b64_e32 v[38:39], 0
	v_mov_b64_e32 v[48:49], 0
	v_mov_b64_e32 v[50:51], 0
	v_mov_b64_e32 v[52:53], 0
	v_mov_b64_e32 v[54:55], 0
	v_mov_b64_e32 v[8:9], 0
	v_mov_b64_e32 v[10:11], 0
	v_mov_b64_e32 v[16:17], 0
	v_mov_b64_e32 v[18:19], 0
	v_mov_b64_e32 v[24:25], 0
	v_mov_b64_e32 v[26:27], 0
	v_mov_b64_e32 v[28:29], 0
	v_mov_b64_e32 v[30:31], 0
	v_mov_b64_e32 v[40:41], 0
	v_mov_b64_e32 v[42:43], 0
	v_mov_b64_e32 v[44:45], 0
	v_mov_b64_e32 v[46:47], 0
	v_mov_b64_e32 v[56:57], 0
	v_mov_b64_e32 v[58:59], 0
	v_mov_b64_e32 v[60:61], 0
	v_mov_b64_e32 v[62:63], 0
	v_mov_b64_e32 v[64:65], 0
	v_mov_b64_e32 v[66:67], 0
	v_mov_b64_e32 v[68:69], 0
	v_mov_b64_e32 v[70:71], 0
	v_mov_b64_e32 v[80:81], 0
	v_mov_b64_e32 v[82:83], 0
	v_mov_b64_e32 v[84:85], 0
	v_mov_b64_e32 v[86:87], 0
	v_mov_b64_e32 v[96:97], 0
	v_mov_b64_e32 v[98:99], 0
	v_mov_b64_e32 v[100:101], 0
	v_mov_b64_e32 v[102:103], 0
	v_mov_b64_e32 v[112:113], 0
	v_mov_b64_e32 v[114:115], 0
	v_mov_b64_e32 v[116:117], 0
	v_mov_b64_e32 v[118:119], 0
	v_mov_b64_e32 v[72:73], 0
	v_mov_b64_e32 v[74:75], 0
	v_mov_b64_e32 v[76:77], 0
	v_mov_b64_e32 v[78:79], 0
	v_mov_b64_e32 v[88:89], 0
	v_mov_b64_e32 v[90:91], 0
	v_mov_b64_e32 v[92:93], 0
	v_mov_b64_e32 v[94:95], 0
	s_waitcnt lgkmcnt(0)
	v_mov_b32_e32 v104, v0
	v_mov_b32_e32 v105, v0
	v_mov_b32_e32 v106, v0
	v_mov_b32_e32 v107, v0
	v_mov_b32_e32 v108, v0
	v_mov_b32_e32 v109, v0
	v_mov_b32_e32 v110, v0
	v_mov_b32_e32 v111, v0
	v_mov_b32_e32 v120, v0
	v_mov_b32_e32 v121, v0
	v_mov_b32_e32 v122, v0
	v_mov_b32_e32 v123, v0
	v_mov_b32_e32 v124, v0
	v_mov_b32_e32 v125, v0
	v_mov_b32_e32 v126, v0
	v_mov_b32_e32 v127, v0

; template <class Epi>
; __device__ __forceinline__ void gemm_phase(LAS unsigned char* lds, const Gemm g, const StaticOrder& S, const Epi& E) {
;     ...
;         const bool has_next = S.next(ui + 1, nxt);
;         const char* nA = has_next ? (const char*)g.A + (size_t)nxt.pm * tstep : cA; const char* nB = has_next ? (const char*)g.Bt + (size_t)nxt.pn * tstep : cB;
;     ...
; #pragma unroll
;         for (int a = 0; a < 2; ++a)
; #pragma unroll
;             for (int b = 0; b < 2; ++b)
; #pragma unroll
;                 for (int m = 0; m < 4; ++m)
; #pragma unroll
;                     for (int n = 0; n < 2; ++n) acc[a][b][m][n] = (f32x4){0.f, 0.f, 0.f, 0.f};
;         cur = nxt; cA = nA; cB = nB; ++ui;
.LBB0_365:
	s_ashr_i32 s19, s18, 31
	v_cmp_lt_i64_e32 vcc, s[20:21], v[194:195]
	s_lshl_b64 s[20:21], s[18:19], 20
	s_add_u32 s20, s87, s20
	s_addc_u32 s21, s76, s21
	s_and_b64 s[22:23], vcc, exec
	s_cselect_b32 s3, s21, s27
	s_cselect_b32 s9, s20, s26
	s_ashr_i32 s1, s0, 31
	s_lshl_b64 s[22:23], s[0:1], 20
	s_add_u32 s22, s90, s22
	s_addc_u32 s23, s91, s23
	s_and_b64 s[30:31], vcc, exec
	s_cselect_b32 s1, s23, s29
	s_cselect_b32 s19, s22, s28
	s_add_u32 s26, s26, 0x80080
	s_addc_u32 s27, s27, 0
	s_add_u32 s34, s28, 0x100
	v_mov_b32_e32 v0, 0
	s_addc_u32 s35, s29, 0
	s_mov_b32 s43, -2
	v_mov_b32_e32 v1, v0
	v_mov_b64_e32 v[2:3], 0
	v_mov_b64_e32 v[4:5], 0
	v_mov_b64_e32 v[6:7], 0
	v_mov_b64_e32 v[16:17], 0
	v_mov_b64_e32 v[18:19], 0
	v_mov_b64_e32 v[20:21], 0
	v_mov_b64_e32 v[22:23], 0
	v_mov_b64_e32 v[32:33], 0
	v_mov_b64_e32 v[34:35], 0
	v_mov_b64_e32 v[36:37], 0
	v_mov_b64_e32 v[38:39], 0
	v_mov_b64_e32 v[48:49], 0
	v_mov_b64_e32 v[50:51], 0
	v_mov_b64_e32 v[52:53], 0
	v_mov_b64_e32 v[54:55], 0
	v_mov_b64_e32 v[8:9], 0
	v_mov_b64_e32 v[10:11], 0
	v_mov_b64_e32 v[12:13], 0
	v_mov_b64_e32 v[14:15], 0
	v_mov_b64_e32 v[24:25], 0
	v_mov_b64_e32 v[26:27], 0
	v_mov_b64_e32 v[28:29], 0
	v_mov_b64_e32 v[30:31], 0
	v_mov_b64_e32 v[40:41], 0
	v_mov_b64_e32 v[42:43], 0
	v_mov_b64_e32 v[44:45], 0
	v_mov_b64_e32 v[46:47], 0
	v_mov_b64_e32 v[56:57], 0
	v_mov_b64_e32 v[58:59], 0
	v_mov_b64_e32 v[60:61], 0
	v_mov_b64_e32 v[62:63], 0
	v_mov_b64_e32 v[64:65], 0
	v_mov_b64_e32 v[66:67], 0
	v_mov_b64_e32 v[68:69], 0
	v_mov_b64_e32 v[70:71], 0
	v_mov_b64_e32 v[80:81], 0
	v_mov_b64_e32 v[82:83], 0
	v_mov_b64_e32 v[84:85], 0
	v_mov_b64_e32 v[86:87], 0
	v_mov_b64_e32 v[96:97], 0
	v_mov_b64_e32 v[98:99], 0
	v_mov_b64_e32 v[100:101], 0
	v_mov_b64_e32 v[102:103], 0
	v_mov_b64_e32 v[112:113], 0
	v_mov_b64_e32 v[114:115], 0
	v_mov_b64_e32 v[116:117], 0
	v_mov_b64_e32 v[118:119], 0
	v_mov_b64_e32 v[72:73], 0
	v_mov_b64_e32 v[74:75], 0
	v_mov_b64_e32 v[76:77], 0
	v_mov_b64_e32 v[78:79], 0
	v_mov_b64_e32 v[88:89], 0
	v_mov_b64_e32 v[90:91], 0
	v_mov_b64_e32 v[92:93], 0
	v_mov_b64_e32 v[94:95], 0
	s_waitcnt lgkmcnt(0)
	v_mov_b32_e32 v104, v0
	v_mov_b32_e32 v105, v0
	v_mov_b32_e32 v106, v0
	v_mov_b32_e32 v107, v0
	v_mov_b32_e32 v108, v0
	v_mov_b32_e32 v109, v0
	v_mov_b32_e32 v110, v0
	v_mov_b32_e32 v111, v0
	v_mov_b32_e32 v120, v0
	v_mov_b32_e32 v121, v0
	v_mov_b32_e32 v122, v0
	v_mov_b32_e32 v123, v0
	v_mov_b32_e32 v124, v0
	v_mov_b32_e32 v125, v0
	v_mov_b32_e32 v126, v0
	v_mov_b32_e32 v127, v0

; template <class Epi>
; __device__ __forceinline__ void gemm_phase(LAS unsigned char* lds, const Gemm g, const StaticOrder& S, const Epi& E) {
;     ...
;         const bool has_next = S.next(ui + 1, nxt);
;         const char* nA = has_next ? (const char*)g.A + (size_t)nxt.pm * tstep : cA; const char* nB = has_next ? (const char*)g.Bt + (size_t)nxt.pn * tstep : cB;
;     ...
; #pragma unroll
;         for (int a = 0; a < 2; ++a)
; #pragma unroll
;             for (int b = 0; b < 2; ++b)
; #pragma unroll
;                 for (int m = 0; m < 4; ++m)
; #pragma unroll
;                     for (int n = 0; n < 2; ++n) acc[a][b][m][n] = (f32x4){0.f, 0.f, 0.f, 0.f};
;         cur = nxt; cA = nA; cB = nB; ++ui;
.LBB0_432:
	s_ashr_i32 s19, s18, 31
	v_cmp_lt_i64_e32 vcc, s[20:21], v[198:199]
	s_lshl_b64 s[20:21], s[18:19], 20
	s_add_u32 s20, s90, s20
	s_addc_u32 s21, s91, s21
	s_and_b64 s[22:23], vcc, exec
	s_cselect_b32 s3, s21, s27
	s_cselect_b32 s9, s20, s26
	s_ashr_i32 s1, s0, 31
	s_lshl_b64 s[22:23], s[0:1], 20
	s_add_u32 s22, s68, s22
	s_addc_u32 s23, s69, s23
	s_and_b64 s[30:31], vcc, exec
	s_cselect_b32 s1, s23, s29
	s_cselect_b32 s19, s22, s28
	s_add_u32 s26, s26, 0x80080
	s_addc_u32 s27, s27, 0
	s_add_u32 s34, s28, 0x100
	v_mov_b32_e32 v0, 0
	s_addc_u32 s35, s29, 0
	s_mov_b32 s43, -2
	v_mov_b32_e32 v1, v0
	v_mov_b64_e32 v[2:3], 0
	v_mov_b64_e32 v[4:5], 0
	v_mov_b64_e32 v[6:7], 0
	v_mov_b64_e32 v[16:17], 0
	v_mov_b64_e32 v[18:19], 0
	v_mov_b64_e32 v[20:21], 0
	v_mov_b64_e32 v[22:23], 0
	v_mov_b64_e32 v[32:33], 0
	v_mov_b64_e32 v[34:35], 0
	v_mov_b64_e32 v[36:37], 0
	v_mov_b64_e32 v[38:39], 0
	v_mov_b64_e32 v[48:49], 0
	v_mov_b64_e32 v[50:51], 0
	v_mov_b64_e32 v[52:53], 0
	v_mov_b64_e32 v[54:55], 0
	v_mov_b64_e32 v[8:9], 0
	v_mov_b64_e32 v[10:11], 0
	v_mov_b64_e32 v[12:13], 0
	v_mov_b64_e32 v[14:15], 0
	v_mov_b64_e32 v[24:25], 0
	v_mov_b64_e32 v[26:27], 0
	v_mov_b64_e32 v[28:29], 0
	v_mov_b64_e32 v[30:31], 0
	v_mov_b64_e32 v[40:41], 0
	v_mov_b64_e32 v[42:43], 0
	v_mov_b64_e32 v[44:45], 0
	v_mov_b64_e32 v[46:47], 0
	v_mov_b64_e32 v[56:57], 0
	v_mov_b64_e32 v[58:59], 0
	v_mov_b64_e32 v[60:61], 0
	v_mov_b64_e32 v[62:63], 0
	v_mov_b64_e32 v[64:65], 0
	v_mov_b64_e32 v[66:67], 0
	v_mov_b64_e32 v[68:69], 0
	v_mov_b64_e32 v[70:71], 0
	v_mov_b64_e32 v[80:81], 0
	v_mov_b64_e32 v[82:83], 0
	v_mov_b64_e32 v[84:85], 0
	v_mov_b64_e32 v[86:87], 0
	v_mov_b64_e32 v[96:97], 0
	v_mov_b64_e32 v[98:99], 0
	v_mov_b64_e32 v[100:101], 0
	v_mov_b64_e32 v[102:103], 0
	v_mov_b64_e32 v[112:113], 0
	v_mov_b64_e32 v[114:115], 0
	v_mov_b64_e32 v[116:117], 0
	v_mov_b64_e32 v[118:119], 0
	v_mov_b64_e32 v[72:73], 0
	v_mov_b64_e32 v[74:75], 0
	v_mov_b64_e32 v[76:77], 0
	v_mov_b64_e32 v[78:79], 0
	v_mov_b64_e32 v[88:89], 0
	v_mov_b64_e32 v[90:91], 0
	v_mov_b64_e32 v[92:93], 0
	v_mov_b64_e32 v[94:95], 0
	s_waitcnt lgkmcnt(0)
	v_mov_b32_e32 v104, v0
	v_mov_b32_e32 v105, v0
	v_mov_b32_e32 v106, v0
	v_mov_b32_e32 v107, v0
	v_mov_b32_e32 v108, v0
	v_mov_b32_e32 v109, v0
	v_mov_b32_e32 v110, v0
	v_mov_b32_e32 v111, v0
	v_mov_b32_e32 v120, v0
	v_mov_b32_e32 v121, v0
	v_mov_b32_e32 v122, v0
	v_mov_b32_e32 v123, v0
	v_mov_b32_e32 v124, v0
	v_mov_b32_e32 v125, v0
	v_mov_b32_e32 v126, v0
	v_mov_b32_e32 v127, v0

; template <class Epi>
; __device__ __forceinline__ void gemm_phase(LAS unsigned char* lds, const Gemm g, const StaticOrder& S, const Epi& E) {
;     ...
;         const bool has_next = S.next(ui + 1, nxt);
;         const char* nA = has_next ? (const char*)g.A + (size_t)nxt.pm * tstep : cA; const char* nB = has_next ? (const char*)g.Bt + (size_t)nxt.pn * tstep : cB;
;     ...
; #pragma unroll
;         for (int a = 0; a < 2; ++a)
; #pragma unroll
;             for (int b = 0; b < 2; ++b)
; #pragma unroll
;                 for (int m = 0; m < 4; ++m)
; #pragma unroll
;                     for (int n = 0; n < 2; ++n) acc[a][b][m][n] = (f32x4){0.f, 0.f, 0.f, 0.f};
;         cur = nxt; cA = nA; cB = nB; ++ui;
.LBB0_489:
	s_ashr_i32 s21, s20, 31
	v_cmp_lt_i64_e32 vcc, s[22:23], v[202:203]
	s_lshl_b64 s[22:23], s[20:21], 20
	s_add_u32 s22, s90, s22
	s_addc_u32 s23, s91, s23
	s_and_b64 s[24:25], vcc, exec
	s_cselect_b32 s3, s23, s9
	s_cselect_b32 s21, s22, s8
	s_ashr_i32 s19, s18, 31
	s_lshl_b64 s[24:25], s[18:19], 20
	s_add_u32 s24, s73, s24
	s_addc_u32 s25, s75, s25
	s_and_b64 s[34:35], vcc, exec
	s_cselect_b32 s19, s25, s31
	s_cselect_b32 s43, s24, s30
	s_add_u32 s8, s8, 0x80080
	s_addc_u32 s9, s9, 0
	s_add_u32 s47, s30, 0x100
	v_mov_b32_e32 v0, 0
	s_addc_u32 s50, s31, 0
	s_mov_b32 s51, -2
	v_mov_b32_e32 v1, v0
	v_mov_b64_e32 v[2:3], 0
	v_mov_b64_e32 v[4:5], 0
	v_mov_b64_e32 v[6:7], 0
	v_mov_b64_e32 v[16:17], 0
	v_mov_b64_e32 v[18:19], 0
	v_mov_b64_e32 v[20:21], 0
	v_mov_b64_e32 v[22:23], 0
	v_mov_b64_e32 v[32:33], 0
	v_mov_b64_e32 v[34:35], 0
	v_mov_b64_e32 v[36:37], 0
	v_mov_b64_e32 v[38:39], 0
	v_mov_b64_e32 v[48:49], 0
	v_mov_b64_e32 v[50:51], 0
	v_mov_b64_e32 v[52:53], 0
	v_mov_b64_e32 v[54:55], 0
	v_mov_b64_e32 v[8:9], 0
	v_mov_b64_e32 v[10:11], 0
	v_mov_b64_e32 v[12:13], 0
	v_mov_b64_e32 v[14:15], 0
	v_mov_b64_e32 v[24:25], 0
	v_mov_b64_e32 v[26:27], 0
	v_mov_b64_e32 v[28:29], 0
	v_mov_b64_e32 v[30:31], 0
	v_mov_b64_e32 v[40:41], 0
	v_mov_b64_e32 v[42:43], 0
	v_mov_b64_e32 v[44:45], 0
	v_mov_b64_e32 v[46:47], 0
	v_mov_b64_e32 v[56:57], 0
	v_mov_b64_e32 v[58:59], 0
	v_mov_b64_e32 v[60:61], 0
	v_mov_b64_e32 v[62:63], 0
	v_mov_b64_e32 v[64:65], 0
	v_mov_b64_e32 v[66:67], 0
	v_mov_b64_e32 v[68:69], 0
	v_mov_b64_e32 v[70:71], 0
	v_mov_b64_e32 v[80:81], 0
	v_mov_b64_e32 v[82:83], 0
	v_mov_b64_e32 v[84:85], 0
	v_mov_b64_e32 v[86:87], 0
	v_mov_b64_e32 v[96:97], 0
	v_mov_b64_e32 v[98:99], 0
	v_mov_b64_e32 v[100:101], 0
	v_mov_b64_e32 v[102:103], 0
	v_mov_b64_e32 v[112:113], 0
	v_mov_b64_e32 v[114:115], 0
	v_mov_b64_e32 v[116:117], 0
	v_mov_b64_e32 v[118:119], 0
	v_mov_b64_e32 v[72:73], 0
	v_mov_b64_e32 v[74:75], 0
	v_mov_b64_e32 v[76:77], 0
	v_mov_b64_e32 v[78:79], 0
	v_mov_b64_e32 v[88:89], 0
	v_mov_b64_e32 v[90:91], 0
	v_mov_b64_e32 v[92:93], 0
	v_mov_b64_e32 v[94:95], 0
	s_waitcnt lgkmcnt(0)
	v_mov_b32_e32 v104, v0
	v_mov_b32_e32 v105, v0
	v_mov_b32_e32 v106, v0
	v_mov_b32_e32 v107, v0
	v_mov_b32_e32 v108, v0
	v_mov_b32_e32 v109, v0
	v_mov_b32_e32 v110, v0
	v_mov_b32_e32 v111, v0
	v_mov_b32_e32 v120, v0
	v_mov_b32_e32 v121, v0
	v_mov_b32_e32 v122, v0
	v_mov_b32_e32 v123, v0
	v_mov_b32_e32 v124, v0
	v_mov_b32_e32 v125, v0
	v_mov_b32_e32 v126, v0
	v_mov_b32_e32 v127, v0

; template <class Epi>
; __device__ __forceinline__ void gemm_phase(LAS unsigned char* lds, const Gemm g, const StaticOrder& S, const Epi& E) {
;     ...
; #pragma unroll
;         for (int a = 0; a < 2; ++a)
; #pragma unroll
;             for (int b = 0; b < 2; ++b)
; #pragma unroll
;                 for (int m = 0; m < 4; ++m)
; #pragma unroll
;                     for (int n = 0; n < 2; ++n) acc[a][b][m][n] = (f32x4){0.f, 0.f, 0.f, 0.f};
;         cur = nxt; cA = nA; cB = nB; ++ui;
.LBB0_590:
	s_add_u32 s0, s0, 0x80
	s_addc_u32 s1, s1, 0
	s_add_u32 s43, s36, 0x100
	v_mov_b32_e32 v0, 0
	s_addc_u32 s63, s37, 0
	s_mov_b32 s8, 0
	v_mov_b32_e32 v1, v0
	v_mov_b64_e32 v[2:3], 0
	v_mov_b64_e32 v[4:5], 0
	v_mov_b64_e32 v[6:7], 0
	v_mov_b64_e32 v[16:17], 0
	v_mov_b64_e32 v[18:19], 0
	v_mov_b64_e32 v[20:21], 0
	v_mov_b64_e32 v[22:23], 0
	v_mov_b64_e32 v[32:33], 0
	v_mov_b64_e32 v[34:35], 0
	v_mov_b64_e32 v[36:37], 0
	v_mov_b64_e32 v[38:39], 0
	v_mov_b64_e32 v[64:65], 0
	v_mov_b64_e32 v[66:67], 0
	v_mov_b64_e32 v[72:73], 0
	v_mov_b64_e32 v[74:75], 0
	v_mov_b64_e32 v[8:9], 0
	v_mov_b64_e32 v[10:11], 0
	v_mov_b64_e32 v[12:13], 0
	v_mov_b64_e32 v[14:15], 0
	v_mov_b64_e32 v[24:25], 0
	v_mov_b64_e32 v[26:27], 0
	v_mov_b64_e32 v[28:29], 0
	v_mov_b64_e32 v[30:31], 0
	v_mov_b64_e32 v[40:41], 0
	v_mov_b64_e32 v[42:43], 0
	v_mov_b64_e32 v[44:45], 0
	v_mov_b64_e32 v[46:47], 0
	v_mov_b64_e32 v[88:89], 0
	v_mov_b64_e32 v[90:91], 0
	v_mov_b64_e32 v[92:93], 0
	v_mov_b64_e32 v[94:95], 0
	v_mov_b64_e32 v[96:97], 0
	v_mov_b64_e32 v[98:99], 0
	v_mov_b64_e32 v[100:101], 0
	v_mov_b64_e32 v[102:103], 0
	v_mov_b64_e32 v[112:113], 0
	v_mov_b64_e32 v[114:115], 0
	v_mov_b64_e32 v[116:117], 0
	v_mov_b64_e32 v[118:119], 0
	v_mov_b64_e32 v[128:129], 0
	v_mov_b64_e32 v[130:131], 0
	v_mov_b64_e32 v[132:133], 0
	v_mov_b64_e32 v[134:135], 0
	v_mov_b64_e32 v[144:145], 0
	v_mov_b64_e32 v[146:147], 0
	v_mov_b64_e32 v[148:149], 0
	v_mov_b64_e32 v[150:151], 0
	s_waitcnt lgkmcnt(0)
	v_mov_b64_e32 v[104:105], 0
	v_mov_b64_e32 v[106:107], 0
	v_mov_b64_e32 v[108:109], 0
	v_mov_b64_e32 v[110:111], 0
	v_mov_b64_e32 v[120:121], 0
	v_mov_b64_e32 v[122:123], 0
	v_mov_b64_e32 v[124:125], 0
	v_mov_b64_e32 v[126:127], 0
	v_mov_b64_e32 v[136:137], 0
	v_mov_b64_e32 v[138:139], 0
	v_mov_b64_e32 v[140:141], 0
	v_mov_b64_e32 v[142:143], 0
	v_mov_b64_e32 v[152:153], 0
	v_mov_b64_e32 v[154:155], 0
	v_mov_b64_e32 v[156:157], 0
	v_mov_b64_e32 v[158:159], 0

; template <class Epi>
; __device__ __forceinline__ void gemm_phase(LAS unsigned char* lds, const Gemm g, const StaticOrder& S, const Epi& E) {
;     ...
;         const bool has_next = S.next(ui + 1, nxt);
;         const char* nA = has_next ? (const char*)g.A + (size_t)nxt.pm * tstep : cA; const char* nB = has_next ? (const char*)g.Bt + (size_t)nxt.pn * tstep : cB;
;     ...
; #pragma unroll
;         for (int a = 0; a < 2; ++a)
; #pragma unroll
;             for (int b = 0; b < 2; ++b)
; #pragma unroll
;                 for (int m = 0; m < 4; ++m)
; #pragma unroll
;                     for (int n = 0; n < 2; ++n) acc[a][b][m][n] = (f32x4){0.f, 0.f, 0.f, 0.f};
;         cur = nxt; cA = nA; cB = nB; ++ui;
.LBB0_720:
	v_mov_b64_e32 v[0:1], 0x1b80
	s_ashr_i32 s9, s8, 31
	v_cmp_lt_i64_e32 vcc, s[10:11], v[0:1]
	s_lshl_b64 s[10:11], s[8:9], 20
	s_add_u32 s10, s90, s10
	s_addc_u32 s11, s91, s11
	s_and_b64 s[12:13], vcc, exec
	s_cselect_b32 s9, s11, s17
	s_cselect_b32 s34, s10, s16
	s_ashr_i32 s1, s0, 31
	s_lshl_b64 s[12:13], s[0:1], 20
	s_add_u32 s12, s80, s12
	s_addc_u32 s13, s81, s13
	s_and_b64 s[20:21], vcc, exec
	s_cselect_b32 s1, s13, s19
	s_cselect_b32 s35, s12, s18
	s_add_u32 s16, s16, 0x80080
	s_addc_u32 s17, s17, 0
	s_add_u32 s36, s18, 0x100
	v_mov_b32_e32 v0, 0
	s_addc_u32 s37, s19, 0
	s_mov_b32 s38, -2
	v_mov_b32_e32 v1, v0
	v_mov_b64_e32 v[2:3], 0
	v_mov_b64_e32 v[8:9], 0
	v_mov_b64_e32 v[10:11], 0
	v_mov_b64_e32 v[16:17], 0
	v_mov_b64_e32 v[18:19], 0
	v_mov_b64_e32 v[24:25], 0
	v_mov_b64_e32 v[26:27], 0
	v_mov_b64_e32 v[32:33], 0
	v_mov_b64_e32 v[34:35], 0
	v_mov_b64_e32 v[40:41], 0
	v_mov_b64_e32 v[42:43], 0
	v_mov_b64_e32 v[48:49], 0
	v_mov_b64_e32 v[50:51], 0
	v_mov_b64_e32 v[56:57], 0
	v_mov_b64_e32 v[58:59], 0
	v_mov_b64_e32 v[4:5], 0
	v_mov_b64_e32 v[6:7], 0
	v_mov_b64_e32 v[12:13], 0
	v_mov_b64_e32 v[14:15], 0
	v_mov_b64_e32 v[20:21], 0
	v_mov_b64_e32 v[22:23], 0
	v_mov_b64_e32 v[28:29], 0
	v_mov_b64_e32 v[30:31], 0
	v_mov_b64_e32 v[36:37], 0
	v_mov_b64_e32 v[38:39], 0
	v_mov_b64_e32 v[44:45], 0
	v_mov_b64_e32 v[46:47], 0
	v_mov_b64_e32 v[52:53], 0
	v_mov_b64_e32 v[54:55], 0
	v_mov_b64_e32 v[60:61], 0
	v_mov_b64_e32 v[62:63], 0
	v_mov_b64_e32 v[64:65], 0
	v_mov_b64_e32 v[66:67], 0
	v_mov_b64_e32 v[72:73], 0
	v_mov_b64_e32 v[74:75], 0
	v_mov_b64_e32 v[80:81], 0
	v_mov_b64_e32 v[82:83], 0
	v_mov_b64_e32 v[88:89], 0
	v_mov_b64_e32 v[90:91], 0
	v_mov_b64_e32 v[96:97], 0
	v_mov_b64_e32 v[98:99], 0
	s_waitcnt lgkmcnt(0)
	v_mov_b64_e32 v[104:105], 0
	v_mov_b64_e32 v[106:107], 0
	v_mov_b64_e32 v[112:113], 0
	v_mov_b64_e32 v[114:115], 0
	v_mov_b64_e32 v[120:121], 0
	v_mov_b64_e32 v[122:123], 0
	v_mov_b64_e32 v[68:69], 0
	v_mov_b64_e32 v[70:71], 0
	v_mov_b64_e32 v[76:77], 0
	v_mov_b64_e32 v[78:79], 0
	v_mov_b64_e32 v[84:85], 0
	v_mov_b64_e32 v[86:87], 0
	v_mov_b64_e32 v[92:93], 0
	v_mov_b64_e32 v[94:95], 0
	v_mov_b64_e32 v[100:101], 0
	v_mov_b64_e32 v[102:103], 0
	v_mov_b64_e32 v[108:109], 0
	v_mov_b64_e32 v[110:111], 0
	v_mov_b64_e32 v[116:117], 0
	v_mov_b64_e32 v[118:119], 0
	v_mov_b64_e32 v[124:125], 0
	v_mov_b64_e32 v[126:127], 0
